# up phase: CUs of each XCD start in 4 groups staggered by s_sleep 33 steps so their epilogue store bursts do not coincide at the L2
# speedup vs baseline: 1.2577x; 1.1235x over previous
;     __host__ __device__ bool next(int i, Unit& u) const {
;         const long L = (long)i * G + c; if (L >= nwg) return false;
;         int wgid = (int)L; { const int q = nwg / NXCD, r = nwg % NXCD, xcd = wgid % NXCD, off = wgid / NXCD; wgid = (xcd < r ? xcd * (q + 1) : r * (q + 1) + (xcd - r) * q) + off; }
;         const int nig = WGM * nN, gid = wgid / nig, fm = gid * WGM, gsz = (nM - fm) < WGM ? (nM - fm) : WGM;
;         u.pm = fm + ((wgid % nig) % gsz); u.pn = (wgid % nig) / gsz; return true;
; __device__ __forceinline__ void build_rstd_table(LAS unsigned char* lds, const float* ssp, const pg8::StaticOrder& S, int tid) {
;     ...
;     for (int k = 0; k < 6; ++k) { pg8::Unit u; ok[k] = S.next((tid >> 8) + 2 * k, u);
;         if (ok[k]) { const f32x4* q = (const f32x4*)(ssp + (size_t)(u.pm * 256 + (tid & 255)) * 16);
; #pragma unroll
;             for (int j = 0; j < 4; ++j) p[k][j] = q[j]; } }
.LBB0_419:
	s_bfe_u32 s100, s96, 0x20003
	s_cmp_eq_u32 s100, 1
	s_cbranch_scc0 .Lstag_1
	s_sleep 33
	s_branch .Lstag_done
.Lstag_1:
	s_cmp_eq_u32 s100, 2
	s_cbranch_scc0 .Lstag_2
	s_sleep 66
	s_branch .Lstag_done
.Lstag_2:
	s_cmp_eq_u32 s100, 3
	s_cbranch_scc0 .Lstag_3
	s_sleep 99
	s_branch .Lstag_done
.Lstag_3:
.Lstag_done:
	s_mov_b64 s[4:5], s[92:93]
	s_load_dwordx4 s[0:3], s[4:5], 0xc8
	v_mov_b32_e32 v96, v145
	s_waitcnt lgkmcnt(0)
	v_mov_b64_e32 v[0:1], s[96:97]
	v_ashrrev_i32_e32 v80, 8, v96
	s_waitcnt lgkmcnt(0)
	s_add_u32 s20, s0, s2
	s_addc_u32 s21, s1, s3
	s_add_u32 s0, s20, 0x10e00000
	v_mad_i64_i32 v[2:3], s[2:3], v80, s69, v[0:1]
	v_and_b32_e32 v81, 0xff, v96
	s_addc_u32 s1, s21, 0
	v_cmp_gt_i64_e32 vcc, s[26:27], v[2:3]
	s_and_saveexec_b64 s[2:3], vcc
	s_cbranch_execz .LBB0_421
	v_ashrrev_i32_e32 v0, 31, v2
	v_lshrrev_b32_e32 v0, 29, v0
	v_add_u32_e32 v0, v2, v0
	v_ashrrev_i32_e32 v1, 3, v0
	v_and_b32_e32 v0, -8, v0
	v_sub_u32_e32 v0, v2, v0
	v_cmp_gt_i32_e64 s[8:9], 0, v0
	s_mov_b32 s4, 0x2e8ba2e9
	s_nop 0
	v_cndmask_b32_e64 v2, v200, v201, s[8:9]
	v_mul_lo_u32 v0, v0, v2
	v_add_u32_e32 v0, v0, v1
	v_mul_hi_i32 v1, v0, s4
	v_lshrrev_b32_e32 v2, 31, v1
	v_ashrrev_i32_e32 v1, 5, v1
	v_add_u32_e32 v1, v1, v2
	v_lshlrev_b32_e32 v2, 3, v1
	v_sub_u32_e32 v3, 0x80, v2
	v_min_i32_e32 v3, 8, v3
	s_waitcnt vmcnt(0)
	v_sub_u32_e32 v4, 0, v3
	v_max_i32_e32 v3, v3, v4
	v_cvt_f32_u32_e32 v4, v3
	s_movk_i32 s4, 0xb0
	v_mul_lo_u32 v1, v1, s4
	v_sub_u32_e32 v0, v0, v1
	v_rcp_iflag_f32_e32 v4, v4
	v_sub_u32_e32 v5, 0, v0
	v_ashrrev_i32_e32 v1, 31, v0
	v_max_i32_e32 v0, v0, v5
	v_mul_f32_e32 v4, 0x4f7ffffe, v4
	v_cvt_u32_f32_e32 v4, v4
	v_sub_u32_e32 v5, 0, v3
	v_mul_lo_u32 v5, v5, v4
	v_mul_hi_u32 v5, v4, v5
	v_add_u32_e32 v4, v4, v5
	v_mul_hi_u32 v4, v0, v4
	v_mul_lo_u32 v4, v4, v3
	v_sub_u32_e32 v0, v0, v4
	v_sub_u32_e32 v4, v0, v3
	v_cmp_ge_u32_e64 s[8:9], v0, v3
	s_nop 1
	v_cndmask_b32_e64 v0, v0, v4, s[8:9]
	v_sub_u32_e32 v4, v0, v3
	v_cmp_ge_u32_e64 s[8:9], v0, v3
	s_nop 1
	v_cndmask_b32_e64 v0, v0, v4, s[8:9]
	v_xor_b32_e32 v0, v0, v1
	v_sub_u32_e32 v0, v0, v1
	v_add_u32_e32 v0, v2, v0
	v_lshl_or_b32 v0, v0, 8, v81
	v_ashrrev_i32_e32 v1, 31, v0
	v_lshlrev_b64 v[0:1], 6, v[0:1]
	v_lshl_add_u64 v[12:13], s[0:1], 0, v[0:1]
	global_load_dwordx4 v[0:3], v[12:13], off offset:48
	global_load_dwordx4 v[4:7], v[12:13], off offset:32
	global_load_dwordx4 v[8:11], v[12:13], off offset:16
	s_nop 0
	global_load_dwordx4 v[12:15], v[12:13], off
